# tiled ACT + K-loop LDS-DMA addresses in SGPR-base form (no per-DMA 64-bit VALU adds) in all three GEMM loops
# speedup vs baseline: 1.0046x; 1.0046x over previous
.LBB0_256:
	s_add_u32 s22, s2, 0xfff80080
	s_addc_u32 s23, s3, -1
	s_add_i32 s48, 0, 0x10000
	s_cmp_eq_u32 s35, 28
	s_cselect_b32 s27, s8, s23
	s_cselect_b32 s26, s9, s22
	s_cselect_b32 s23, s15, s34
	s_cselect_b32 s22, s17, s33
	s_add_i32 s50, 0, 0x14000
	v_add_u32_e32 v176, s48, v191
	v_add_u32_e32 v188, s50, v191
	ds_read_b128 v[148:151], v176
	ds_read_b128 v[152:155], v176 offset:1024
	ds_read_b128 v[172:175], v176 offset:2048
	ds_read_b128 v[176:179], v176 offset:3072
	ds_read_b128 v[180:183], v188
	ds_read_b128 v[184:187], v188 offset:1024
	ds_read_b128 v[196:199], v188 offset:2048
	ds_read_b128 v[200:203], v188 offset:3072
	s_add_i32 m0, s39, 0xc000
	ds_read_b128 v[204:207], v194
	ds_read_b128 v[212:215], v194 offset:1024
	ds_read_b128 v[216:219], v194 offset:2048
	ds_read_b128 v[220:223], v194 offset:3072
	ds_read_b128 v[224:227], v194 offset:4096
	ds_read_b128 v[228:231], v194 offset:5120
	ds_read_b128 v[232:235], v194 offset:6144
	ds_read_b128 v[236:239], v194 offset:7168
	global_load_lds_dwordx4 v168, s[2:3]
	s_add_i32 m0, s39, 0xe000
	s_nop 0
	global_load_lds_dwordx4 v170, s[2:3]
	s_waitcnt vmcnt(8)
	s_waitcnt lgkmcnt(0)
	s_barrier
	s_setprio 1
	s_waitcnt lgkmcnt(0)
	v_mfma_f32_16x16x32_bf16 v[144:147], v[148:151], v[204:207], v[144:147]
	v_mfma_f32_16x16x32_bf16 v[136:139], v[172:175], v[204:207], v[136:139]
	v_mfma_f32_16x16x32_bf16 v[128:131], v[148:151], v[216:219], v[128:131]
	v_mfma_f32_16x16x32_bf16 v[120:123], v[172:175], v[216:219], v[120:123]
	v_mfma_f32_16x16x32_bf16 v[112:115], v[148:151], v[224:227], v[112:115]
	v_mfma_f32_16x16x32_bf16 v[104:107], v[172:175], v[224:227], v[104:107]
	v_mfma_f32_16x16x32_bf16 v[96:99], v[148:151], v[232:235], v[96:99]
	v_mfma_f32_16x16x32_bf16 v[88:91], v[172:175], v[232:235], v[88:91]
	v_mfma_f32_16x16x32_bf16 v[144:147], v[152:155], v[212:215], v[144:147]
	v_mfma_f32_16x16x32_bf16 v[136:139], v[176:179], v[212:215], v[136:139]
	v_mfma_f32_16x16x32_bf16 v[128:131], v[152:155], v[220:223], v[128:131]
	v_mfma_f32_16x16x32_bf16 v[120:123], v[176:179], v[220:223], v[120:123]
	v_mfma_f32_16x16x32_bf16 v[112:115], v[152:155], v[228:231], v[112:115]
	v_mfma_f32_16x16x32_bf16 v[104:107], v[176:179], v[228:231], v[104:107]
	v_mfma_f32_16x16x32_bf16 v[96:99], v[152:155], v[236:239], v[96:99]
	v_mfma_f32_16x16x32_bf16 v[88:91], v[176:179], v[236:239], v[88:91]
	s_setprio 0
	s_setprio 1
	v_mfma_f32_16x16x32_bf16 v[140:143], v[180:183], v[204:207], v[140:143]
	v_mfma_f32_16x16x32_bf16 v[132:135], v[196:199], v[204:207], v[132:135]
	v_mfma_f32_16x16x32_bf16 v[124:127], v[180:183], v[216:219], v[124:127]
	v_mfma_f32_16x16x32_bf16 v[116:119], v[196:199], v[216:219], v[116:119]
	v_mfma_f32_16x16x32_bf16 v[108:111], v[180:183], v[224:227], v[108:111]
	v_mfma_f32_16x16x32_bf16 v[100:103], v[196:199], v[224:227], v[100:103]
	v_mfma_f32_16x16x32_bf16 v[92:95], v[180:183], v[232:235], v[92:95]
	v_mfma_f32_16x16x32_bf16 v[84:87], v[196:199], v[232:235], v[84:87]
	v_mfma_f32_16x16x32_bf16 v[140:143], v[184:187], v[212:215], v[140:143]
	v_mfma_f32_16x16x32_bf16 v[132:135], v[200:203], v[212:215], v[132:135]
	v_mfma_f32_16x16x32_bf16 v[124:127], v[184:187], v[220:223], v[124:127]
	v_mfma_f32_16x16x32_bf16 v[116:119], v[200:203], v[220:223], v[116:119]
	v_mfma_f32_16x16x32_bf16 v[108:111], v[184:187], v[228:231], v[108:111]
	v_mfma_f32_16x16x32_bf16 v[100:103], v[200:203], v[228:231], v[100:103]
	v_mfma_f32_16x16x32_bf16 v[92:95], v[184:187], v[236:239], v[92:95]
	v_mfma_f32_16x16x32_bf16 v[84:87], v[200:203], v[236:239], v[84:87]
	s_setprio 0
	s_barrier
	s_add_i32 s48, s48, s28
	s_add_u32 s98, s22, 0x80
	s_addc_u32 s99, s23, 0
	s_add_u32 s100, s26, 0x80
	s_addc_u32 s101, s27, 0
	s_mov_b32 m0, s48
	ds_read_b128 v[204:207], v194 offset:16384
	ds_read_b128 v[212:215], v194 offset:17408
	ds_read_b128 v[216:219], v194 offset:18432
	ds_read_b128 v[220:223], v194 offset:19456
	ds_read_b128 v[224:227], v194 offset:20480
	ds_read_b128 v[228:231], v194 offset:21504
	ds_read_b128 v[232:235], v194 offset:22528
	ds_read_b128 v[236:239], v194 offset:23552
	global_load_lds_dwordx4 v2, s[22:23]
	s_add_i32 m0, s48, 0x2000
	s_add_u32 s48, s22, 0x80000
	s_addc_u32 s49, s23, 0
	s_add_i32 s50, s50, s28
	global_load_lds_dwordx4 v156, s[22:23]
	s_mov_b32 m0, s50
	s_nop 0
	global_load_lds_dwordx4 v2, s[48:49]
	s_add_i32 m0, s50, 0x2000
	s_nop 0
	global_load_lds_dwordx4 v156, s[48:49]
	s_mov_b32 m0, s39
	s_nop 0
	global_load_lds_dwordx4 v160, s[26:27]
	s_mov_b32 m0, s41
	s_nop 0
	global_load_lds_dwordx4 v158, s[26:27]
	s_waitcnt vmcnt(8)
	s_waitcnt lgkmcnt(0)
	s_barrier
	s_setprio 1
	s_waitcnt lgkmcnt(0)
	v_mfma_f32_16x16x32_bf16 v[80:83], v[148:151], v[204:207], v[80:83]
	v_mfma_f32_16x16x32_bf16 v[72:75], v[172:175], v[204:207], v[72:75]
	v_mfma_f32_16x16x32_bf16 v[64:67], v[148:151], v[216:219], v[64:67]
	v_mfma_f32_16x16x32_bf16 v[56:59], v[172:175], v[216:219], v[56:59]
	v_mfma_f32_16x16x32_bf16 v[48:51], v[148:151], v[224:227], v[48:51]
	v_mfma_f32_16x16x32_bf16 v[40:43], v[172:175], v[224:227], v[40:43]
	v_mfma_f32_16x16x32_bf16 v[32:35], v[148:151], v[232:235], v[32:35]
	v_mfma_f32_16x16x32_bf16 v[24:27], v[172:175], v[232:235], v[24:27]
	v_mfma_f32_16x16x32_bf16 v[80:83], v[152:155], v[212:215], v[80:83]
	v_mfma_f32_16x16x32_bf16 v[72:75], v[176:179], v[212:215], v[72:75]
	v_mfma_f32_16x16x32_bf16 v[64:67], v[152:155], v[220:223], v[64:67]
	v_mfma_f32_16x16x32_bf16 v[56:59], v[176:179], v[220:223], v[56:59]
	v_mfma_f32_16x16x32_bf16 v[48:51], v[152:155], v[228:231], v[48:51]
	v_mfma_f32_16x16x32_bf16 v[40:43], v[176:179], v[228:231], v[40:43]
	v_mfma_f32_16x16x32_bf16 v[32:35], v[152:155], v[236:239], v[32:35]
	v_mfma_f32_16x16x32_bf16 v[24:27], v[176:179], v[236:239], v[24:27]
	s_setprio 0
	s_setprio 1
	v_mfma_f32_16x16x32_bf16 v[76:79], v[180:183], v[204:207], v[76:79]
	v_mfma_f32_16x16x32_bf16 v[68:71], v[196:199], v[204:207], v[68:71]
	v_mfma_f32_16x16x32_bf16 v[60:63], v[180:183], v[216:219], v[60:63]
	v_mfma_f32_16x16x32_bf16 v[52:55], v[196:199], v[216:219], v[52:55]
	v_mfma_f32_16x16x32_bf16 v[44:47], v[180:183], v[224:227], v[44:47]
	v_mfma_f32_16x16x32_bf16 v[36:39], v[196:199], v[224:227], v[36:39]
	v_mfma_f32_16x16x32_bf16 v[28:31], v[180:183], v[232:235], v[28:31]
	v_mfma_f32_16x16x32_bf16 v[20:23], v[196:199], v[232:235], v[20:23]
	v_mfma_f32_16x16x32_bf16 v[76:79], v[184:187], v[212:215], v[76:79]
	v_mfma_f32_16x16x32_bf16 v[68:71], v[200:203], v[212:215], v[68:71]
	v_mfma_f32_16x16x32_bf16 v[60:63], v[184:187], v[220:223], v[60:63]
	v_mfma_f32_16x16x32_bf16 v[52:55], v[200:203], v[220:223], v[52:55]
	v_mfma_f32_16x16x32_bf16 v[44:47], v[184:187], v[228:231], v[44:47]
	v_mfma_f32_16x16x32_bf16 v[36:39], v[200:203], v[228:231], v[36:39]
	v_mfma_f32_16x16x32_bf16 v[28:31], v[184:187], v[236:239], v[28:31]
	v_mfma_f32_16x16x32_bf16 v[20:23], v[200:203], v[236:239], v[20:23]
	s_setprio 0
	s_barrier
	s_add_i32 s48, 0, 0x18000
	s_add_i32 s49, 0, 0x1c000
	v_add_u32_e32 v176, s48, v191
	v_add_u32_e32 v195, s49, v191
	ds_read_b128 v[148:151], v176
	ds_read_b128 v[152:155], v176 offset:1024
	ds_read_b128 v[172:175], v176 offset:2048
	ds_read_b128 v[176:179], v176 offset:3072
	ds_read_b128 v[180:183], v195
	ds_read_b128 v[184:187], v195 offset:1024
	ds_read_b128 v[196:199], v195 offset:2048
	ds_read_b128 v[200:203], v195 offset:3072
	s_add_u32 s26, s26, 0x80000
	s_addc_u32 s27, s27, 0
	s_mov_b32 m0, s42
	ds_read_b128 v[204:207], v194 offset:32768
	ds_read_b128 v[212:215], v194 offset:33792
	ds_read_b128 v[216:219], v194 offset:34816
	ds_read_b128 v[220:223], v194 offset:35840
	ds_read_b128 v[224:227], v194 offset:36864
	ds_read_b128 v[228:231], v194 offset:37888
	ds_read_b128 v[232:235], v194 offset:38912
	ds_read_b128 v[236:239], v194 offset:39936
	global_load_lds_dwordx4 v160, s[26:27]
	s_mov_b32 m0, s43
	s_nop 0
	global_load_lds_dwordx4 v158, s[26:27]
	s_waitcnt vmcnt(8)
	s_waitcnt lgkmcnt(0)
	s_barrier
	s_setprio 1
	s_waitcnt lgkmcnt(0)
	v_mfma_f32_16x16x32_bf16 v[144:147], v[148:151], v[204:207], v[144:147]
	v_mfma_f32_16x16x32_bf16 v[136:139], v[172:175], v[204:207], v[136:139]
	v_mfma_f32_16x16x32_bf16 v[128:131], v[148:151], v[216:219], v[128:131]
	v_mfma_f32_16x16x32_bf16 v[120:123], v[172:175], v[216:219], v[120:123]
	v_mfma_f32_16x16x32_bf16 v[112:115], v[148:151], v[224:227], v[112:115]
	v_mfma_f32_16x16x32_bf16 v[104:107], v[172:175], v[224:227], v[104:107]
	v_mfma_f32_16x16x32_bf16 v[96:99], v[148:151], v[232:235], v[96:99]
	v_mfma_f32_16x16x32_bf16 v[88:91], v[172:175], v[232:235], v[88:91]
	v_mfma_f32_16x16x32_bf16 v[144:147], v[152:155], v[212:215], v[144:147]
	v_mfma_f32_16x16x32_bf16 v[136:139], v[176:179], v[212:215], v[136:139]
	v_mfma_f32_16x16x32_bf16 v[128:131], v[152:155], v[220:223], v[128:131]
	v_mfma_f32_16x16x32_bf16 v[120:123], v[176:179], v[220:223], v[120:123]
	v_mfma_f32_16x16x32_bf16 v[112:115], v[152:155], v[228:231], v[112:115]
	v_mfma_f32_16x16x32_bf16 v[104:107], v[176:179], v[228:231], v[104:107]
	v_mfma_f32_16x16x32_bf16 v[96:99], v[152:155], v[236:239], v[96:99]
	v_mfma_f32_16x16x32_bf16 v[88:91], v[176:179], v[236:239], v[88:91]
	s_setprio 0
	s_setprio 1
	v_mfma_f32_16x16x32_bf16 v[140:143], v[180:183], v[204:207], v[140:143]
	v_mfma_f32_16x16x32_bf16 v[132:135], v[196:199], v[204:207], v[132:135]
	v_mfma_f32_16x16x32_bf16 v[124:127], v[180:183], v[216:219], v[124:127]
	v_mfma_f32_16x16x32_bf16 v[116:119], v[196:199], v[216:219], v[116:119]
	v_mfma_f32_16x16x32_bf16 v[108:111], v[180:183], v[224:227], v[108:111]
	v_mfma_f32_16x16x32_bf16 v[100:103], v[196:199], v[224:227], v[100:103]
	v_mfma_f32_16x16x32_bf16 v[92:95], v[180:183], v[232:235], v[92:95]
	v_mfma_f32_16x16x32_bf16 v[84:87], v[196:199], v[232:235], v[84:87]
	v_mfma_f32_16x16x32_bf16 v[140:143], v[184:187], v[212:215], v[140:143]
	v_mfma_f32_16x16x32_bf16 v[132:135], v[200:203], v[212:215], v[132:135]
	v_mfma_f32_16x16x32_bf16 v[124:127], v[184:187], v[220:223], v[124:127]
	v_mfma_f32_16x16x32_bf16 v[116:119], v[200:203], v[220:223], v[116:119]
	v_mfma_f32_16x16x32_bf16 v[108:111], v[184:187], v[228:231], v[108:111]
	v_mfma_f32_16x16x32_bf16 v[100:103], v[200:203], v[228:231], v[100:103]
	v_mfma_f32_16x16x32_bf16 v[92:95], v[184:187], v[236:239], v[92:95]
	v_mfma_f32_16x16x32_bf16 v[84:87], v[200:203], v[236:239], v[84:87]
	s_setprio 0
	s_barrier
	s_add_i32 s26, s48, s28
	s_mov_b32 m0, s26
	ds_read_b128 v[204:207], v194 offset:49152
	ds_read_b128 v[212:215], v194 offset:50176
	ds_read_b128 v[216:219], v194 offset:51200
	ds_read_b128 v[220:223], v194 offset:52224
	ds_read_b128 v[224:227], v194 offset:53248
	ds_read_b128 v[228:231], v194 offset:54272
	ds_read_b128 v[232:235], v194 offset:55296
	ds_read_b128 v[236:239], v194 offset:56320
	global_load_lds_dwordx4 v2, s[98:99]
	s_add_i32 m0, s26, 0x2000
	s_add_u32 s22, s22, 0x80080
	s_addc_u32 s23, s23, 0
	s_add_i32 s26, s49, s28
	global_load_lds_dwordx4 v156, s[98:99]
	s_mov_b32 m0, s26
	s_nop 0
	global_load_lds_dwordx4 v2, s[22:23]
	s_add_i32 m0, s26, 0x2000
	s_nop 0
	global_load_lds_dwordx4 v156, s[22:23]
	s_mov_b32 m0, s44
	s_nop 0
	global_load_lds_dwordx4 v160, s[100:101]
	s_mov_b32 m0, s45
	s_nop 0
	global_load_lds_dwordx4 v158, s[100:101]
	s_waitcnt vmcnt(8)
	s_waitcnt lgkmcnt(0)
	s_barrier
	s_setprio 1
	s_waitcnt lgkmcnt(0)
	v_mfma_f32_16x16x32_bf16 v[80:83], v[148:151], v[204:207], v[80:83]
	v_mfma_f32_16x16x32_bf16 v[72:75], v[172:175], v[204:207], v[72:75]
	v_mfma_f32_16x16x32_bf16 v[64:67], v[148:151], v[216:219], v[64:67]
	v_mfma_f32_16x16x32_bf16 v[56:59], v[172:175], v[216:219], v[56:59]
	v_mfma_f32_16x16x32_bf16 v[48:51], v[148:151], v[224:227], v[48:51]
	v_mfma_f32_16x16x32_bf16 v[40:43], v[172:175], v[224:227], v[40:43]
	v_mfma_f32_16x16x32_bf16 v[32:35], v[148:151], v[232:235], v[32:35]
	v_mfma_f32_16x16x32_bf16 v[24:27], v[172:175], v[232:235], v[24:27]
	v_mfma_f32_16x16x32_bf16 v[80:83], v[152:155], v[212:215], v[80:83]
	v_mfma_f32_16x16x32_bf16 v[72:75], v[176:179], v[212:215], v[72:75]
	v_mfma_f32_16x16x32_bf16 v[64:67], v[152:155], v[220:223], v[64:67]
	v_mfma_f32_16x16x32_bf16 v[56:59], v[176:179], v[220:223], v[56:59]
	v_mfma_f32_16x16x32_bf16 v[48:51], v[152:155], v[228:231], v[48:51]
	v_mfma_f32_16x16x32_bf16 v[40:43], v[176:179], v[228:231], v[40:43]
	v_mfma_f32_16x16x32_bf16 v[32:35], v[152:155], v[236:239], v[32:35]
	v_mfma_f32_16x16x32_bf16 v[24:27], v[176:179], v[236:239], v[24:27]
	s_setprio 0
	s_setprio 1
	v_mfma_f32_16x16x32_bf16 v[76:79], v[180:183], v[204:207], v[76:79]
	v_mfma_f32_16x16x32_bf16 v[68:71], v[196:199], v[204:207], v[68:71]
	v_mfma_f32_16x16x32_bf16 v[60:63], v[180:183], v[216:219], v[60:63]
	v_mfma_f32_16x16x32_bf16 v[52:55], v[196:199], v[216:219], v[52:55]
	v_mfma_f32_16x16x32_bf16 v[44:47], v[180:183], v[224:227], v[44:47]
	v_mfma_f32_16x16x32_bf16 v[36:39], v[196:199], v[224:227], v[36:39]
	v_mfma_f32_16x16x32_bf16 v[28:31], v[180:183], v[232:235], v[28:31]
	v_mfma_f32_16x16x32_bf16 v[20:23], v[196:199], v[232:235], v[20:23]
	v_mfma_f32_16x16x32_bf16 v[76:79], v[184:187], v[212:215], v[76:79]
	v_mfma_f32_16x16x32_bf16 v[68:71], v[200:203], v[212:215], v[68:71]
	v_mfma_f32_16x16x32_bf16 v[60:63], v[184:187], v[220:223], v[60:63]
	v_mfma_f32_16x16x32_bf16 v[52:55], v[200:203], v[220:223], v[52:55]
	v_mfma_f32_16x16x32_bf16 v[44:47], v[184:187], v[228:231], v[44:47]
	v_mfma_f32_16x16x32_bf16 v[36:39], v[200:203], v[228:231], v[36:39]
	v_mfma_f32_16x16x32_bf16 v[28:31], v[184:187], v[236:239], v[28:31]
	v_mfma_f32_16x16x32_bf16 v[20:23], v[200:203], v[236:239], v[20:23]
	s_setprio 0
	s_barrier
	s_add_i32 s35, s35, 2
	s_add_u32 s2, s2, 0x100
	s_addc_u32 s3, s3, 0
	s_add_u32 s33, s33, 0x100
	s_addc_u32 s34, s34, 0
	s_cmp_gt_u32 s35, 29
	s_cbranch_scc0 .LBB0_256
	s_and_b64 vcc, exec, s[12:13]
	s_cbranch_vccz .LBB0_259
	s_barrier

.LBB0_489:
	s_add_u32 s26, s22, 0xfff80080
	s_addc_u32 s27, s23, -1
	s_add_i32 s34, 0, 0x10000
	s_cmp_eq_u32 s33, 28
	s_cselect_b32 s39, s3, s27
	s_cselect_b32 s38, s6, s26
	s_cselect_b32 s27, s8, s17
	s_cselect_b32 s26, s9, s15
	s_add_i32 s53, 0, 0x14000
	v_add_u32_e32 v144, s34, v168
	v_add_u32_e32 v160, s53, v168
	ds_read_b128 v[4:7], v144
	ds_read_b128 v[8:11], v144 offset:1024
	ds_read_b128 v[140:143], v144 offset:2048
	ds_read_b128 v[144:147], v144 offset:3072
	ds_read_b128 v[172:175], v160
	ds_read_b128 v[176:179], v160 offset:1024
	ds_read_b128 v[180:183], v160 offset:2048
	ds_read_b128 v[184:187], v160 offset:3072
	s_add_i32 m0, s13, 0xc000
	ds_read_b128 v[188:191], v170
	ds_read_b128 v[192:195], v170 offset:1024
	ds_read_b128 v[196:199], v170 offset:2048
	ds_read_b128 v[200:203], v170 offset:3072
	ds_read_b128 v[204:207], v170 offset:4096
	ds_read_b128 v[212:215], v170 offset:5120
	ds_read_b128 v[216:219], v170 offset:6144
	ds_read_b128 v[220:223], v170 offset:7168
	global_load_lds_dwordx4 v156, s[22:23]
	s_add_i32 m0, s13, 0xe000
	s_nop 0
	global_load_lds_dwordx4 v158, s[22:23]
	s_waitcnt vmcnt(8)
	s_waitcnt lgkmcnt(0)
	s_barrier
	s_setprio 1
	s_waitcnt lgkmcnt(0)
	v_mfma_f32_16x16x32_bf16 v[136:139], v[4:7], v[188:191], v[136:139]
	v_mfma_f32_16x16x32_bf16 v[132:135], v[140:143], v[188:191], v[132:135]
	v_mfma_f32_16x16x32_bf16 v[128:131], v[4:7], v[196:199], v[128:131]
	v_mfma_f32_16x16x32_bf16 v[120:123], v[140:143], v[196:199], v[120:123]
	v_mfma_f32_16x16x32_bf16 v[112:115], v[4:7], v[204:207], v[112:115]
	v_mfma_f32_16x16x32_bf16 v[104:107], v[140:143], v[204:207], v[104:107]
	v_mfma_f32_16x16x32_bf16 v[96:99], v[4:7], v[216:219], v[96:99]
	v_mfma_f32_16x16x32_bf16 v[88:91], v[140:143], v[216:219], v[88:91]
	v_mfma_f32_16x16x32_bf16 v[136:139], v[8:11], v[192:195], v[136:139]
	v_mfma_f32_16x16x32_bf16 v[132:135], v[144:147], v[192:195], v[132:135]
	v_mfma_f32_16x16x32_bf16 v[128:131], v[8:11], v[200:203], v[128:131]
	v_mfma_f32_16x16x32_bf16 v[120:123], v[144:147], v[200:203], v[120:123]
	v_mfma_f32_16x16x32_bf16 v[112:115], v[8:11], v[212:215], v[112:115]
	v_mfma_f32_16x16x32_bf16 v[104:107], v[144:147], v[212:215], v[104:107]
	v_mfma_f32_16x16x32_bf16 v[96:99], v[8:11], v[220:223], v[96:99]
	v_mfma_f32_16x16x32_bf16 v[88:91], v[144:147], v[220:223], v[88:91]
	s_setprio 0
	s_setprio 1
	v_mfma_f32_16x16x32_bf16 v[124:127], v[172:175], v[188:191], v[124:127]
	v_mfma_f32_16x16x32_bf16 v[116:119], v[180:183], v[188:191], v[116:119]
	v_mfma_f32_16x16x32_bf16 v[108:111], v[172:175], v[196:199], v[108:111]
	v_mfma_f32_16x16x32_bf16 v[100:103], v[180:183], v[196:199], v[100:103]
	v_mfma_f32_16x16x32_bf16 v[92:95], v[172:175], v[204:207], v[92:95]
	v_mfma_f32_16x16x32_bf16 v[84:87], v[180:183], v[204:207], v[84:87]
	v_mfma_f32_16x16x32_bf16 v[80:83], v[172:175], v[216:219], v[80:83]
	v_mfma_f32_16x16x32_bf16 v[76:79], v[180:183], v[216:219], v[76:79]
	v_mfma_f32_16x16x32_bf16 v[124:127], v[176:179], v[192:195], v[124:127]
	v_mfma_f32_16x16x32_bf16 v[116:119], v[184:187], v[192:195], v[116:119]
	v_mfma_f32_16x16x32_bf16 v[108:111], v[176:179], v[200:203], v[108:111]
	v_mfma_f32_16x16x32_bf16 v[100:103], v[184:187], v[200:203], v[100:103]
	v_mfma_f32_16x16x32_bf16 v[92:95], v[176:179], v[212:215], v[92:95]
	v_mfma_f32_16x16x32_bf16 v[84:87], v[184:187], v[212:215], v[84:87]
	v_mfma_f32_16x16x32_bf16 v[80:83], v[176:179], v[220:223], v[80:83]
	v_mfma_f32_16x16x32_bf16 v[76:79], v[184:187], v[220:223], v[76:79]
	s_setprio 0
	s_barrier
	s_add_i32 s34, s34, s7
	s_add_u32 s98, s26, 0x80
	s_addc_u32 s99, s27, 0
	s_add_u32 s100, s38, 0x80
	s_addc_u32 s101, s39, 0
	s_mov_b32 m0, s34
	ds_read_b128 v[188:191], v170 offset:16384
	ds_read_b128 v[192:195], v170 offset:17408
	ds_read_b128 v[196:199], v170 offset:18432
	ds_read_b128 v[200:203], v170 offset:19456
	ds_read_b128 v[204:207], v170 offset:20480
	ds_read_b128 v[212:215], v170 offset:21504
	ds_read_b128 v[216:219], v170 offset:22528
	ds_read_b128 v[220:223], v170 offset:23552
	global_load_lds_dwordx4 v2, s[26:27]
	s_add_i32 m0, s34, 0x2000
	s_add_u32 s34, s26, 0x80000
	s_addc_u32 s35, s27, 0
	s_add_i32 s53, s53, s7
	global_load_lds_dwordx4 v148, s[26:27]
	s_mov_b32 m0, s53
	s_nop 0
	global_load_lds_dwordx4 v2, s[34:35]
	s_add_i32 m0, s53, 0x2000
	s_nop 0
	global_load_lds_dwordx4 v148, s[34:35]
	s_mov_b32 m0, s13
	s_nop 0
	global_load_lds_dwordx4 v152, s[38:39]
	s_mov_b32 m0, s46
	s_nop 0
	global_load_lds_dwordx4 v150, s[38:39]
	s_waitcnt vmcnt(8)
	s_waitcnt lgkmcnt(0)
	s_barrier
	s_setprio 1
	s_waitcnt lgkmcnt(0)
	v_mfma_f32_16x16x32_bf16 v[72:75], v[4:7], v[188:191], v[72:75]
	v_mfma_f32_16x16x32_bf16 v[68:71], v[140:143], v[188:191], v[68:71]
	v_mfma_f32_16x16x32_bf16 v[64:67], v[4:7], v[196:199], v[64:67]
	v_mfma_f32_16x16x32_bf16 v[56:59], v[140:143], v[196:199], v[56:59]
	v_mfma_f32_16x16x32_bf16 v[48:51], v[4:7], v[204:207], v[48:51]
	v_mfma_f32_16x16x32_bf16 v[40:43], v[140:143], v[204:207], v[40:43]
	v_mfma_f32_16x16x32_bf16 v[4:7], v[4:7], v[216:219], v[32:35]
	v_mfma_f32_16x16x32_bf16 v[72:75], v[8:11], v[192:195], v[72:75]
	v_mfma_f32_16x16x32_bf16 v[68:71], v[144:147], v[192:195], v[68:71]
	v_mfma_f32_16x16x32_bf16 v[64:67], v[8:11], v[200:203], v[64:67]
	v_mfma_f32_16x16x32_bf16 v[56:59], v[144:147], v[200:203], v[56:59]
	v_mfma_f32_16x16x32_bf16 v[48:51], v[8:11], v[212:215], v[48:51]
	v_mfma_f32_16x16x32_bf16 v[40:43], v[144:147], v[212:215], v[40:43]
	v_mfma_f32_16x16x32_bf16 v[4:7], v[8:11], v[220:223], v[4:7]
	v_mfma_f32_16x16x32_bf16 v[8:11], v[140:143], v[216:219], v[24:27]
	v_mfma_f32_16x16x32_bf16 v[8:11], v[144:147], v[220:223], v[8:11]
	s_setprio 0
	s_setprio 1
	v_mfma_f32_16x16x32_bf16 v[24:27], v[172:175], v[188:191], v[60:63]
	v_mfma_f32_16x16x32_bf16 v[60:63], v[176:179], v[192:195], v[24:27]
	v_mfma_f32_16x16x32_bf16 v[24:27], v[180:183], v[188:191], v[52:55]
	v_mfma_f32_16x16x32_bf16 v[52:55], v[184:187], v[192:195], v[24:27]
	v_mfma_f32_16x16x32_bf16 v[24:27], v[172:175], v[196:199], v[44:47]
	v_mfma_f32_16x16x32_bf16 v[44:47], v[176:179], v[200:203], v[24:27]
	v_mfma_f32_16x16x32_bf16 v[24:27], v[180:183], v[196:199], v[36:39]
	v_mfma_f32_16x16x32_bf16 v[36:39], v[184:187], v[200:203], v[24:27]
	v_mfma_f32_16x16x32_bf16 v[24:27], v[172:175], v[204:207], v[28:31]
	v_mfma_f32_16x16x32_bf16 v[20:23], v[180:183], v[204:207], v[20:23]
	v_mfma_f32_16x16x32_bf16 v[16:19], v[172:175], v[216:219], v[16:19]
	v_mfma_f32_16x16x32_bf16 v[12:15], v[180:183], v[216:219], v[12:15]
	v_mfma_f32_16x16x32_bf16 v[28:31], v[176:179], v[212:215], v[24:27]
	v_mfma_f32_16x16x32_bf16 v[20:23], v[184:187], v[212:215], v[20:23]
	v_mfma_f32_16x16x32_bf16 v[16:19], v[176:179], v[220:223], v[16:19]
	v_mfma_f32_16x16x32_bf16 v[12:15], v[184:187], v[220:223], v[12:15]
	s_setprio 0
	s_barrier
	s_add_i32 s53, 0, 0x18000
	s_add_i32 s54, 0, 0x1c000
	v_add_u32_e32 v144, s53, v168
	v_add_u32_e32 v171, s54, v168
	ds_read_b128 v[24:27], v144
	ds_read_b128 v[32:35], v144 offset:1024
	ds_read_b128 v[140:143], v144 offset:2048
	ds_read_b128 v[144:147], v144 offset:3072
	ds_read_b128 v[172:175], v171
	ds_read_b128 v[176:179], v171 offset:1024
	ds_read_b128 v[180:183], v171 offset:2048
	ds_read_b128 v[184:187], v171 offset:3072
	s_add_u32 s34, s38, 0x80000
	s_addc_u32 s35, s39, 0
	s_mov_b32 m0, s47
	ds_read_b128 v[188:191], v170 offset:32768
	ds_read_b128 v[192:195], v170 offset:33792
	ds_read_b128 v[196:199], v170 offset:34816
	ds_read_b128 v[200:203], v170 offset:35840
	ds_read_b128 v[204:207], v170 offset:36864
	ds_read_b128 v[212:215], v170 offset:37888
	ds_read_b128 v[216:219], v170 offset:38912
	ds_read_b128 v[220:223], v170 offset:39936
	global_load_lds_dwordx4 v152, s[34:35]
	s_mov_b32 m0, s48
	s_nop 0
	global_load_lds_dwordx4 v150, s[34:35]
	s_waitcnt vmcnt(8)
	s_waitcnt lgkmcnt(0)
	s_barrier
	s_setprio 1
	s_waitcnt lgkmcnt(0)
	v_mfma_f32_16x16x32_bf16 v[136:139], v[24:27], v[188:191], v[136:139]
	v_mfma_f32_16x16x32_bf16 v[132:135], v[140:143], v[188:191], v[132:135]
	v_mfma_f32_16x16x32_bf16 v[128:131], v[24:27], v[196:199], v[128:131]
	v_mfma_f32_16x16x32_bf16 v[120:123], v[140:143], v[196:199], v[120:123]
	v_mfma_f32_16x16x32_bf16 v[112:115], v[24:27], v[204:207], v[112:115]
	v_mfma_f32_16x16x32_bf16 v[104:107], v[140:143], v[204:207], v[104:107]
	v_mfma_f32_16x16x32_bf16 v[96:99], v[24:27], v[216:219], v[96:99]
	v_mfma_f32_16x16x32_bf16 v[88:91], v[140:143], v[216:219], v[88:91]
	v_mfma_f32_16x16x32_bf16 v[136:139], v[32:35], v[192:195], v[136:139]
	v_mfma_f32_16x16x32_bf16 v[132:135], v[144:147], v[192:195], v[132:135]
	v_mfma_f32_16x16x32_bf16 v[128:131], v[32:35], v[200:203], v[128:131]
	v_mfma_f32_16x16x32_bf16 v[120:123], v[144:147], v[200:203], v[120:123]
	v_mfma_f32_16x16x32_bf16 v[112:115], v[32:35], v[212:215], v[112:115]
	v_mfma_f32_16x16x32_bf16 v[104:107], v[144:147], v[212:215], v[104:107]
	v_mfma_f32_16x16x32_bf16 v[96:99], v[32:35], v[220:223], v[96:99]
	v_mfma_f32_16x16x32_bf16 v[88:91], v[144:147], v[220:223], v[88:91]
	s_setprio 0
	s_setprio 1
	v_mfma_f32_16x16x32_bf16 v[124:127], v[172:175], v[188:191], v[124:127]
	v_mfma_f32_16x16x32_bf16 v[116:119], v[180:183], v[188:191], v[116:119]
	v_mfma_f32_16x16x32_bf16 v[108:111], v[172:175], v[196:199], v[108:111]
	v_mfma_f32_16x16x32_bf16 v[100:103], v[180:183], v[196:199], v[100:103]
	v_mfma_f32_16x16x32_bf16 v[92:95], v[172:175], v[204:207], v[92:95]
	v_mfma_f32_16x16x32_bf16 v[84:87], v[180:183], v[204:207], v[84:87]
	v_mfma_f32_16x16x32_bf16 v[80:83], v[172:175], v[216:219], v[80:83]
	v_mfma_f32_16x16x32_bf16 v[76:79], v[180:183], v[216:219], v[76:79]
	v_mfma_f32_16x16x32_bf16 v[124:127], v[176:179], v[192:195], v[124:127]
	v_mfma_f32_16x16x32_bf16 v[116:119], v[184:187], v[192:195], v[116:119]
	v_mfma_f32_16x16x32_bf16 v[108:111], v[176:179], v[200:203], v[108:111]
	v_mfma_f32_16x16x32_bf16 v[100:103], v[184:187], v[200:203], v[100:103]
	v_mfma_f32_16x16x32_bf16 v[92:95], v[176:179], v[212:215], v[92:95]
	v_mfma_f32_16x16x32_bf16 v[84:87], v[184:187], v[212:215], v[84:87]
	v_mfma_f32_16x16x32_bf16 v[80:83], v[176:179], v[220:223], v[80:83]
	v_mfma_f32_16x16x32_bf16 v[76:79], v[184:187], v[220:223], v[76:79]
	s_setprio 0
	s_barrier
	s_add_i32 s34, s53, s7
	s_mov_b32 m0, s34
	ds_read_b128 v[188:191], v170 offset:49152
	ds_read_b128 v[192:195], v170 offset:50176
	ds_read_b128 v[196:199], v170 offset:51200
	ds_read_b128 v[200:203], v170 offset:52224
	ds_read_b128 v[204:207], v170 offset:53248
	ds_read_b128 v[212:215], v170 offset:54272
	ds_read_b128 v[216:219], v170 offset:55296
	ds_read_b128 v[220:223], v170 offset:56320
	global_load_lds_dwordx4 v2, s[98:99]
	s_add_i32 m0, s34, 0x2000
	s_add_u32 s26, s26, 0x80080
	s_addc_u32 s27, s27, 0
	s_add_i32 s34, s54, s7
	global_load_lds_dwordx4 v148, s[98:99]
	s_mov_b32 m0, s34
	s_nop 0
	global_load_lds_dwordx4 v2, s[26:27]
	s_add_i32 m0, s34, 0x2000
	s_nop 0
	global_load_lds_dwordx4 v148, s[26:27]
	s_mov_b32 m0, s49
	s_nop 0
	global_load_lds_dwordx4 v152, s[100:101]
	s_mov_b32 m0, s50
	s_nop 0
	global_load_lds_dwordx4 v150, s[100:101]
	s_waitcnt vmcnt(8)
	s_waitcnt lgkmcnt(0)
	s_barrier
	s_setprio 1
	s_waitcnt lgkmcnt(0)
	v_mfma_f32_16x16x32_bf16 v[72:75], v[24:27], v[188:191], v[72:75]
	v_mfma_f32_16x16x32_bf16 v[64:67], v[24:27], v[196:199], v[64:67]
	v_mfma_f32_16x16x32_bf16 v[48:51], v[24:27], v[204:207], v[48:51]
	v_mfma_f32_16x16x32_bf16 v[4:7], v[24:27], v[216:219], v[4:7]
	v_mfma_f32_16x16x32_bf16 v[72:75], v[32:35], v[192:195], v[72:75]
	v_mfma_f32_16x16x32_bf16 v[68:71], v[140:143], v[188:191], v[68:71]
	v_mfma_f32_16x16x32_bf16 v[64:67], v[32:35], v[200:203], v[64:67]
	v_mfma_f32_16x16x32_bf16 v[56:59], v[140:143], v[196:199], v[56:59]
	v_mfma_f32_16x16x32_bf16 v[48:51], v[32:35], v[212:215], v[48:51]
	v_mfma_f32_16x16x32_bf16 v[40:43], v[140:143], v[204:207], v[40:43]
	v_mfma_f32_16x16x32_bf16 v[32:35], v[32:35], v[220:223], v[4:7]
	v_mfma_f32_16x16x32_bf16 v[4:7], v[140:143], v[216:219], v[8:11]
	v_mfma_f32_16x16x32_bf16 v[68:71], v[144:147], v[192:195], v[68:71]
	v_mfma_f32_16x16x32_bf16 v[56:59], v[144:147], v[200:203], v[56:59]
	v_mfma_f32_16x16x32_bf16 v[40:43], v[144:147], v[212:215], v[40:43]
	v_mfma_f32_16x16x32_bf16 v[24:27], v[144:147], v[220:223], v[4:7]
	s_setprio 0
	s_setprio 1
	v_mfma_f32_16x16x32_bf16 v[4:7], v[172:175], v[188:191], v[60:63]
	v_mfma_f32_16x16x32_bf16 v[60:63], v[176:179], v[192:195], v[4:7]
	v_mfma_f32_16x16x32_bf16 v[4:7], v[180:183], v[188:191], v[52:55]
	v_mfma_f32_16x16x32_bf16 v[52:55], v[184:187], v[192:195], v[4:7]
	v_mfma_f32_16x16x32_bf16 v[4:7], v[172:175], v[196:199], v[44:47]
	v_mfma_f32_16x16x32_bf16 v[44:47], v[176:179], v[200:203], v[4:7]
	v_mfma_f32_16x16x32_bf16 v[4:7], v[180:183], v[196:199], v[36:39]
	v_mfma_f32_16x16x32_bf16 v[36:39], v[184:187], v[200:203], v[4:7]
	v_mfma_f32_16x16x32_bf16 v[4:7], v[172:175], v[204:207], v[28:31]
	v_mfma_f32_16x16x32_bf16 v[28:31], v[176:179], v[212:215], v[4:7]
	v_mfma_f32_16x16x32_bf16 v[4:7], v[180:183], v[204:207], v[20:23]
	v_mfma_f32_16x16x32_bf16 v[20:23], v[184:187], v[212:215], v[4:7]
	v_mfma_f32_16x16x32_bf16 v[4:7], v[172:175], v[216:219], v[16:19]
	v_mfma_f32_16x16x32_bf16 v[16:19], v[176:179], v[220:223], v[4:7]
	v_mfma_f32_16x16x32_bf16 v[4:7], v[180:183], v[216:219], v[12:15]
	v_mfma_f32_16x16x32_bf16 v[12:15], v[184:187], v[220:223], v[4:7]
	s_setprio 0
	s_barrier
	s_add_i32 s33, s33, 2
	s_add_u32 s22, s22, 0x100
	s_addc_u32 s23, s23, 0
	s_add_u32 s15, s15, 0x100
	s_addc_u32 s17, s17, 0
	s_cmp_gt_u32 s33, 29
	s_cbranch_scc0 .LBB0_489
	s_and_b64 vcc, exec, s[4:5]
	s_cbranch_vccz .LBB0_492
	s_barrier

.LBB0_832:
	s_add_i32 s28, s9, 2
	s_add_u32 s22, s2, s100
	s_addc_u32 s23, s3, 0
	s_add_i32 s29, 0, 0x10000
	s_cmp_eq_u32 s52, s9
	s_cselect_b32 s23, s1, s23
	s_cselect_b32 s22, s0, s22
	v_add_u32_e32 v2, s29, v147
	s_cselect_b32 s35, s21, s8
	s_cselect_b32 s34, s20, s7
	s_add_i32 s9, 0, 0x14000
	ds_read_b128 v[152:155], v2
	ds_read_b128 v[156:159], v2 offset:1024
	ds_read_b128 v[160:163], v2 offset:2048
	ds_read_b128 v[168:171], v2 offset:3072
	v_add_u32_e32 v2, s9, v147
	ds_read_b128 v[172:175], v2
	ds_read_b128 v[176:179], v2 offset:1024
	ds_read_b128 v[180:183], v2 offset:2048
	ds_read_b128 v[184:187], v2 offset:3072
	s_add_i32 m0, s47, 0xc000
	ds_read_b128 v[188:191], v150
	ds_read_b128 v[192:195], v150 offset:1024
	ds_read_b128 v[196:199], v150 offset:2048
	ds_read_b128 v[200:203], v150 offset:3072
	ds_read_b128 v[204:207], v150 offset:4096
	ds_read_b128 v[210:213], v150 offset:5120
	ds_read_b128 v[214:217], v150 offset:6144
	ds_read_b128 v[218:221], v150 offset:7168
	global_load_lds_dwordx4 v140, s[2:3]
	s_add_i32 m0, s47, 0xe000
	s_nop 0
	global_load_lds_dwordx4 v142, s[2:3]
	s_waitcnt vmcnt(8)
	s_waitcnt lgkmcnt(0)
	s_barrier
	s_setprio 1
	s_waitcnt lgkmcnt(0)
	v_mfma_f32_16x16x32_bf16 v[128:131], v[152:155], v[188:191], v[128:131]
	v_mfma_f32_16x16x32_bf16 v[124:127], v[160:163], v[188:191], v[124:127]
	v_mfma_f32_16x16x32_bf16 v[112:115], v[152:155], v[196:199], v[112:115]
	v_mfma_f32_16x16x32_bf16 v[108:111], v[160:163], v[196:199], v[108:111]
	v_mfma_f32_16x16x32_bf16 v[96:99], v[152:155], v[204:207], v[96:99]
	v_mfma_f32_16x16x32_bf16 v[92:95], v[160:163], v[204:207], v[92:95]
	v_mfma_f32_16x16x32_bf16 v[80:83], v[152:155], v[214:217], v[80:83]
	v_mfma_f32_16x16x32_bf16 v[76:79], v[160:163], v[214:217], v[76:79]
	v_mfma_f32_16x16x32_bf16 v[128:131], v[156:159], v[192:195], v[128:131]
	v_mfma_f32_16x16x32_bf16 v[124:127], v[168:171], v[192:195], v[124:127]
	v_mfma_f32_16x16x32_bf16 v[112:115], v[156:159], v[200:203], v[112:115]
	v_mfma_f32_16x16x32_bf16 v[108:111], v[168:171], v[200:203], v[108:111]
	v_mfma_f32_16x16x32_bf16 v[96:99], v[156:159], v[210:213], v[96:99]
	v_mfma_f32_16x16x32_bf16 v[92:95], v[168:171], v[210:213], v[92:95]
	v_mfma_f32_16x16x32_bf16 v[80:83], v[156:159], v[218:221], v[80:83]
	v_mfma_f32_16x16x32_bf16 v[76:79], v[168:171], v[218:221], v[76:79]
	s_setprio 0
	s_setprio 1
	v_mfma_f32_16x16x32_bf16 v[120:123], v[172:175], v[188:191], v[120:123]
	v_mfma_f32_16x16x32_bf16 v[116:119], v[180:183], v[188:191], v[116:119]
	v_mfma_f32_16x16x32_bf16 v[104:107], v[172:175], v[196:199], v[104:107]
	v_mfma_f32_16x16x32_bf16 v[100:103], v[180:183], v[196:199], v[100:103]
	v_mfma_f32_16x16x32_bf16 v[88:91], v[172:175], v[204:207], v[88:91]
	v_mfma_f32_16x16x32_bf16 v[84:87], v[180:183], v[204:207], v[84:87]
	v_mfma_f32_16x16x32_bf16 v[72:75], v[172:175], v[214:217], v[72:75]
	v_mfma_f32_16x16x32_bf16 v[68:71], v[180:183], v[214:217], v[68:71]
	v_mfma_f32_16x16x32_bf16 v[120:123], v[176:179], v[192:195], v[120:123]
	v_mfma_f32_16x16x32_bf16 v[116:119], v[184:187], v[192:195], v[116:119]
	v_mfma_f32_16x16x32_bf16 v[104:107], v[176:179], v[200:203], v[104:107]
	v_mfma_f32_16x16x32_bf16 v[100:103], v[184:187], v[200:203], v[100:103]
	v_mfma_f32_16x16x32_bf16 v[88:91], v[176:179], v[210:213], v[88:91]
	v_mfma_f32_16x16x32_bf16 v[84:87], v[184:187], v[210:213], v[84:87]
	v_mfma_f32_16x16x32_bf16 v[72:75], v[176:179], v[218:221], v[72:75]
	v_mfma_f32_16x16x32_bf16 v[68:71], v[184:187], v[218:221], v[68:71]
	s_setprio 0
	s_barrier
	s_add_i32 s29, s29, s26
	s_mov_b32 m0, s29
	ds_read_b128 v[188:191], v150 offset:16384
	ds_read_b128 v[192:195], v150 offset:17408
	ds_read_b128 v[196:199], v150 offset:18432
	ds_read_b128 v[200:203], v150 offset:19456
	ds_read_b128 v[204:207], v150 offset:20480
	ds_read_b128 v[210:213], v150 offset:21504
	ds_read_b128 v[214:217], v150 offset:22528
	ds_read_b128 v[218:221], v150 offset:23552
	global_load_lds_dwordx4 v136, s[34:35]
	s_add_i32 m0, s29, 0x2000
	s_add_i32 s9, s9, s26
	global_load_lds_dwordx4 v132, s[34:35]
	s_add_u32 s34, s34, s16
	s_addc_u32 s35, s35, 0
	s_mov_b32 m0, s9
	s_nop 0
	global_load_lds_dwordx4 v136, s[34:35]
	s_add_i32 m0, s9, 0x2000
	s_nop 0
	global_load_lds_dwordx4 v132, s[34:35]
	s_mov_b32 m0, s47
	s_nop 0
	global_load_lds_dwordx4 v138, s[22:23]
	s_mov_b32 m0, s48
	s_nop 0
	global_load_lds_dwordx4 v134, s[22:23]
	s_waitcnt vmcnt(8)
	s_waitcnt lgkmcnt(0)
	s_barrier
	s_setprio 1
	s_waitcnt lgkmcnt(0)
	v_mfma_f32_16x16x32_bf16 v[64:67], v[152:155], v[188:191], v[64:67]
	v_mfma_f32_16x16x32_bf16 v[60:63], v[160:163], v[188:191], v[60:63]
	v_mfma_f32_16x16x32_bf16 v[48:51], v[152:155], v[196:199], v[48:51]
	v_mfma_f32_16x16x32_bf16 v[44:47], v[160:163], v[196:199], v[44:47]
	v_mfma_f32_16x16x32_bf16 v[32:35], v[152:155], v[204:207], v[32:35]
	v_mfma_f32_16x16x32_bf16 v[28:31], v[160:163], v[204:207], v[28:31]
	v_mfma_f32_16x16x32_bf16 v[16:19], v[152:155], v[214:217], v[16:19]
	v_mfma_f32_16x16x32_bf16 v[12:15], v[160:163], v[214:217], v[12:15]
	v_mfma_f32_16x16x32_bf16 v[64:67], v[156:159], v[192:195], v[64:67]
	v_mfma_f32_16x16x32_bf16 v[60:63], v[168:171], v[192:195], v[60:63]
	v_mfma_f32_16x16x32_bf16 v[48:51], v[156:159], v[200:203], v[48:51]
	v_mfma_f32_16x16x32_bf16 v[44:47], v[168:171], v[200:203], v[44:47]
	v_mfma_f32_16x16x32_bf16 v[32:35], v[156:159], v[210:213], v[32:35]
	v_mfma_f32_16x16x32_bf16 v[28:31], v[168:171], v[210:213], v[28:31]
	v_mfma_f32_16x16x32_bf16 v[16:19], v[156:159], v[218:221], v[16:19]
	v_mfma_f32_16x16x32_bf16 v[12:15], v[168:171], v[218:221], v[12:15]
	s_setprio 0
	s_setprio 1
	v_mfma_f32_16x16x32_bf16 v[56:59], v[172:175], v[188:191], v[56:59]
	v_mfma_f32_16x16x32_bf16 v[52:55], v[180:183], v[188:191], v[52:55]
	v_mfma_f32_16x16x32_bf16 v[40:43], v[172:175], v[196:199], v[40:43]
	v_mfma_f32_16x16x32_bf16 v[36:39], v[180:183], v[196:199], v[36:39]
	v_mfma_f32_16x16x32_bf16 v[24:27], v[172:175], v[204:207], v[24:27]
	v_mfma_f32_16x16x32_bf16 v[20:23], v[180:183], v[204:207], v[20:23]
	v_mfma_f32_16x16x32_bf16 v[8:11], v[172:175], v[214:217], v[8:11]
	v_mfma_f32_16x16x32_bf16 v[4:7], v[180:183], v[214:217], v[4:7]
	v_mfma_f32_16x16x32_bf16 v[56:59], v[176:179], v[192:195], v[56:59]
	v_mfma_f32_16x16x32_bf16 v[52:55], v[184:187], v[192:195], v[52:55]
	v_mfma_f32_16x16x32_bf16 v[40:43], v[176:179], v[200:203], v[40:43]
	v_mfma_f32_16x16x32_bf16 v[36:39], v[184:187], v[200:203], v[36:39]
	v_mfma_f32_16x16x32_bf16 v[24:27], v[176:179], v[210:213], v[24:27]
	v_mfma_f32_16x16x32_bf16 v[20:23], v[184:187], v[210:213], v[20:23]
	v_mfma_f32_16x16x32_bf16 v[8:11], v[176:179], v[218:221], v[8:11]
	v_mfma_f32_16x16x32_bf16 v[4:7], v[184:187], v[218:221], v[4:7]
	s_setprio 0
	s_barrier
	s_add_i32 s9, 0, 0x18000
	v_add_u32_e32 v2, s9, v147
	s_add_i32 s29, 0, 0x1c000
	ds_read_b128 v[152:155], v2
	ds_read_b128 v[156:159], v2 offset:1024
	ds_read_b128 v[160:163], v2 offset:2048
	ds_read_b128 v[168:171], v2 offset:3072
	v_add_u32_e32 v2, s29, v147
	ds_read_b128 v[172:175], v2
	ds_read_b128 v[176:179], v2 offset:1024
	ds_read_b128 v[180:183], v2 offset:2048
	ds_read_b128 v[184:187], v2 offset:3072
	s_add_u32 s22, s22, s16
	s_addc_u32 s23, s23, 0
	s_mov_b32 m0, s49
	ds_read_b128 v[188:191], v150 offset:32768
	ds_read_b128 v[192:195], v150 offset:33792
	ds_read_b128 v[196:199], v150 offset:34816
	ds_read_b128 v[200:203], v150 offset:35840
	ds_read_b128 v[204:207], v150 offset:36864
	ds_read_b128 v[210:213], v150 offset:37888
	ds_read_b128 v[214:217], v150 offset:38912
	ds_read_b128 v[218:221], v150 offset:39936
	global_load_lds_dwordx4 v138, s[22:23]
	s_mov_b32 m0, s50
	s_nop 0
	global_load_lds_dwordx4 v134, s[22:23]
	s_waitcnt vmcnt(8)
	s_waitcnt lgkmcnt(0)
	s_barrier
	s_setprio 1
	s_waitcnt lgkmcnt(0)
	v_mfma_f32_16x16x32_bf16 v[128:131], v[152:155], v[188:191], v[128:131]
	v_mfma_f32_16x16x32_bf16 v[124:127], v[160:163], v[188:191], v[124:127]
	v_mfma_f32_16x16x32_bf16 v[112:115], v[152:155], v[196:199], v[112:115]
	v_mfma_f32_16x16x32_bf16 v[108:111], v[160:163], v[196:199], v[108:111]
	v_mfma_f32_16x16x32_bf16 v[96:99], v[152:155], v[204:207], v[96:99]
	v_mfma_f32_16x16x32_bf16 v[92:95], v[160:163], v[204:207], v[92:95]
	v_mfma_f32_16x16x32_bf16 v[80:83], v[152:155], v[214:217], v[80:83]
	v_mfma_f32_16x16x32_bf16 v[76:79], v[160:163], v[214:217], v[76:79]
	v_mfma_f32_16x16x32_bf16 v[128:131], v[156:159], v[192:195], v[128:131]
	v_mfma_f32_16x16x32_bf16 v[124:127], v[168:171], v[192:195], v[124:127]
	v_mfma_f32_16x16x32_bf16 v[112:115], v[156:159], v[200:203], v[112:115]
	v_mfma_f32_16x16x32_bf16 v[108:111], v[168:171], v[200:203], v[108:111]
	v_mfma_f32_16x16x32_bf16 v[96:99], v[156:159], v[210:213], v[96:99]
	v_mfma_f32_16x16x32_bf16 v[92:95], v[168:171], v[210:213], v[92:95]
	v_mfma_f32_16x16x32_bf16 v[80:83], v[156:159], v[218:221], v[80:83]
	v_mfma_f32_16x16x32_bf16 v[76:79], v[168:171], v[218:221], v[76:79]
	s_setprio 0
	s_setprio 1
	v_mfma_f32_16x16x32_bf16 v[120:123], v[172:175], v[188:191], v[120:123]
	v_mfma_f32_16x16x32_bf16 v[116:119], v[180:183], v[188:191], v[116:119]
	v_mfma_f32_16x16x32_bf16 v[104:107], v[172:175], v[196:199], v[104:107]
	v_mfma_f32_16x16x32_bf16 v[100:103], v[180:183], v[196:199], v[100:103]
	v_mfma_f32_16x16x32_bf16 v[88:91], v[172:175], v[204:207], v[88:91]
	v_mfma_f32_16x16x32_bf16 v[84:87], v[180:183], v[204:207], v[84:87]
	v_mfma_f32_16x16x32_bf16 v[72:75], v[172:175], v[214:217], v[72:75]
	v_mfma_f32_16x16x32_bf16 v[68:71], v[180:183], v[214:217], v[68:71]
	v_mfma_f32_16x16x32_bf16 v[120:123], v[176:179], v[192:195], v[120:123]
	v_mfma_f32_16x16x32_bf16 v[116:119], v[184:187], v[192:195], v[116:119]
	v_mfma_f32_16x16x32_bf16 v[104:107], v[176:179], v[200:203], v[104:107]
	v_mfma_f32_16x16x32_bf16 v[100:103], v[184:187], v[200:203], v[100:103]
	v_mfma_f32_16x16x32_bf16 v[88:91], v[176:179], v[210:213], v[88:91]
	v_mfma_f32_16x16x32_bf16 v[84:87], v[184:187], v[210:213], v[84:87]
	v_mfma_f32_16x16x32_bf16 v[72:75], v[176:179], v[218:221], v[72:75]
	v_mfma_f32_16x16x32_bf16 v[68:71], v[184:187], v[218:221], v[68:71]
	s_setprio 0
	s_barrier
	s_add_i32 s9, s9, s26
	s_mov_b32 m0, s9
	ds_read_b128 v[188:191], v150 offset:49152
	ds_read_b128 v[192:195], v150 offset:50176
	ds_read_b128 v[196:199], v150 offset:51200
	ds_read_b128 v[200:203], v150 offset:52224
	ds_read_b128 v[204:207], v150 offset:53248
	ds_read_b128 v[210:213], v150 offset:54272
	ds_read_b128 v[214:217], v150 offset:55296
	ds_read_b128 v[218:221], v150 offset:56320
	s_sub_u32 s34, s34, s16
	s_subb_u32 s35, s35, 0
	s_add_u32 s34, s34, 0x80
	s_addc_u32 s35, s35, 0
	global_load_lds_dwordx4 v136, s[34:35]
	s_add_i32 m0, s9, 0x2000
	s_add_i32 s9, s29, s26
	global_load_lds_dwordx4 v132, s[34:35]
	s_mov_b32 m0, s9
	s_nop 0
	s_add_u32 s34, s34, s16
	s_addc_u32 s35, s35, 0
	global_load_lds_dwordx4 v136, s[34:35]
	s_add_i32 m0, s9, 0x2000
	s_nop 0
	global_load_lds_dwordx4 v132, s[34:35]
	s_mov_b32 m0, s53
	s_nop 0
	s_sub_u32 s22, s22, s16
	s_subb_u32 s23, s23, 0
	s_add_u32 s22, s22, s100
	s_addc_u32 s23, s23, 0
	global_load_lds_dwordx4 v138, s[22:23]
	s_mov_b32 m0, s54
	s_nop 0
	global_load_lds_dwordx4 v134, s[22:23]
	s_waitcnt vmcnt(8)
	s_waitcnt lgkmcnt(0)
	s_barrier
	s_setprio 1
	s_waitcnt lgkmcnt(0)
	v_mfma_f32_16x16x32_bf16 v[64:67], v[152:155], v[188:191], v[64:67]
	v_mfma_f32_16x16x32_bf16 v[60:63], v[160:163], v[188:191], v[60:63]
	v_mfma_f32_16x16x32_bf16 v[48:51], v[152:155], v[196:199], v[48:51]
	v_mfma_f32_16x16x32_bf16 v[44:47], v[160:163], v[196:199], v[44:47]
	v_mfma_f32_16x16x32_bf16 v[32:35], v[152:155], v[204:207], v[32:35]
	v_mfma_f32_16x16x32_bf16 v[28:31], v[160:163], v[204:207], v[28:31]
	v_mfma_f32_16x16x32_bf16 v[16:19], v[152:155], v[214:217], v[16:19]
	v_mfma_f32_16x16x32_bf16 v[12:15], v[160:163], v[214:217], v[12:15]
	v_mfma_f32_16x16x32_bf16 v[64:67], v[156:159], v[192:195], v[64:67]
	v_mfma_f32_16x16x32_bf16 v[60:63], v[168:171], v[192:195], v[60:63]
	v_mfma_f32_16x16x32_bf16 v[48:51], v[156:159], v[200:203], v[48:51]
	v_mfma_f32_16x16x32_bf16 v[44:47], v[168:171], v[200:203], v[44:47]
	v_mfma_f32_16x16x32_bf16 v[32:35], v[156:159], v[210:213], v[32:35]
	v_mfma_f32_16x16x32_bf16 v[28:31], v[168:171], v[210:213], v[28:31]
	v_mfma_f32_16x16x32_bf16 v[16:19], v[156:159], v[218:221], v[16:19]
	v_mfma_f32_16x16x32_bf16 v[12:15], v[168:171], v[218:221], v[12:15]
	s_setprio 0
	s_setprio 1
	v_mfma_f32_16x16x32_bf16 v[56:59], v[172:175], v[188:191], v[56:59]
	v_mfma_f32_16x16x32_bf16 v[52:55], v[180:183], v[188:191], v[52:55]
	v_mfma_f32_16x16x32_bf16 v[40:43], v[172:175], v[196:199], v[40:43]
	v_mfma_f32_16x16x32_bf16 v[36:39], v[180:183], v[196:199], v[36:39]
	v_mfma_f32_16x16x32_bf16 v[24:27], v[172:175], v[204:207], v[24:27]
	v_mfma_f32_16x16x32_bf16 v[20:23], v[180:183], v[204:207], v[20:23]
	v_mfma_f32_16x16x32_bf16 v[8:11], v[172:175], v[214:217], v[8:11]
	v_mfma_f32_16x16x32_bf16 v[4:7], v[180:183], v[214:217], v[4:7]
	v_mfma_f32_16x16x32_bf16 v[56:59], v[176:179], v[192:195], v[56:59]
	v_mfma_f32_16x16x32_bf16 v[52:55], v[184:187], v[192:195], v[52:55]
	v_mfma_f32_16x16x32_bf16 v[40:43], v[176:179], v[200:203], v[40:43]
	v_mfma_f32_16x16x32_bf16 v[36:39], v[184:187], v[200:203], v[36:39]
	v_mfma_f32_16x16x32_bf16 v[24:27], v[176:179], v[210:213], v[24:27]
	v_mfma_f32_16x16x32_bf16 v[20:23], v[184:187], v[210:213], v[20:23]
	v_mfma_f32_16x16x32_bf16 v[8:11], v[176:179], v[218:221], v[8:11]
	v_mfma_f32_16x16x32_bf16 v[4:7], v[184:187], v[218:221], v[4:7]
	s_setprio 0
	s_barrier
	s_add_u32 s2, s2, s98
	s_addc_u32 s3, s3, 0
	s_add_u32 s7, s7, 0x100
	s_addc_u32 s8, s8, 0
	s_cmp_ge_u32 s28, s51
	s_mov_b32 s9, s28
	s_cbranch_scc0 .LBB0_832
	s_and_b64 vcc, exec, s[18:19]
	s_cbranch_vccz .LBB0_835
	s_barrier
